# weight-conversion job loops: next job loads stay in flight during the current job transposition (wait moved to the consumer)
# speedup vs baseline: 1.0079x; 1.0079x over previous
; #define LAS __attribute__((address_space(3)))
; __device__ __forceinline__ unsigned cvt_pk_bf16(float lo, float hi) { unsigned r; asm volatile("v_cvt_pk_bf16_f32 %0, %1, %2" : "=v"(r) : "v"(lo), "v"(hi)); return r; }
; __device__ __forceinline__ void cvt_store(const CvtJob& j, int tid, const f32x4 (&v)[8], const float (&gk)[8], LAS unsigned char* lds) {
;     LAS bf16_t* T = (LAS bf16_t*)lds;
;     {
;         const int nq = tid & 31, kk = tid >> 5;
; #pragma unroll
;         for (int i = 0; i < 8; ++i) {
;             const int k = kk + 16 * i;
; #pragma unroll
;             for (int jj = 0; jj < 4; ++jj) { const unsigned w = cvt_pk_bf16(v[i][jj] * gk[i], 0.f); T[(jj * 32 + nq) * 130 + k] = (bf16_t)(w & 0xffffu); }
;         }
;     }
;     __syncthreads();
;     {
;         const int n = tid >> 2, kc = tid & 3, rs_ = (n & 3) * 32 + (n >> 2);
;         const LAS unsigned* T32 = (const LAS unsigned*)lds;
;         bf16_t* d = j.dst + (size_t)(j.n0 + n) * j.K + j.k0 + kc * 32;
; template <bool PREPMAP>
; __device__ __forceinline__ void convert_jobs(const Params& p, int job0, int job_end, int stride, LAS unsigned char* lds) {
;     ...
;     for (;;) {
;         const int nj = job + stride; const bool more = nj < job_end;
;         CvtJob nxt = cur; f32x4 v2[8]; float gk2[8];
;         if (more) { nxt = cvt_decode(p, cvt_map<PREPMAP>(nj)); cvt_load(nxt, tid, v2, gk2); }
.LBB0_104:
	s_load_dwordx2 s[38:39], s[0:1], 0xa0
	s_load_dwordx2 s[40:41], s[0:1], 0x88
	s_load_dwordx4 s[16:19], s[0:1], 0x68
	s_load_dwordx2 s[42:43], s[0:1], 0x58
	s_load_dwordx4 s[20:23], s[0:1], 0x10
	s_load_dwordx8 s[8:15], s[0:1], 0x28
	v_and_b32_e32 v34, 31, v36
	v_ashrrev_i32_e32 v91, 2, v36
	v_bfe_u32 v89, v37, 5, 2
	v_and_b32_e32 v90, 28, v37
	v_mul_u32_u24_e32 v37, 0x104, v34
	v_lshlrev_b32_e32 v34, 5, v91
	v_and_b32_e32 v38, 3, v36
	v_and_b32_e32 v34, 0x60, v34
	v_ashrrev_i32_e32 v36, 4, v36
	s_movk_i32 s4, 0x104
	v_add_u32_e32 v36, v34, v36
	v_mul_lo_u32 v36, v36, s4
	v_lshl_add_u32 v35, v68, 1, 0
	v_lshlrev_b32_e32 v34, 5, v38
	v_add_u32_e32 v36, 0, v36
	v_lshlrev_b32_e32 v38, 6, v38
	v_mov_b32_e32 v71, 0
	s_movk_i32 s60, 0x3ff
	s_movk_i32 s61, 0xc0
	s_movk_i32 s62, 0x141f
	s_movk_i32 s63, 0x1427
	s_movk_i32 s64, 0x1480
	v_add_u32_e32 v92, v35, v37
	v_lshlrev_b32_e32 v72, 1, v34
	v_add_u32_e32 v93, v36, v38
	s_waitcnt vmcnt(0)
	s_branch .LBB0_106

; #define LAS __attribute__((address_space(3)))
; __device__ __forceinline__ unsigned cvt_pk_bf16(float lo, float hi) { unsigned r; asm volatile("v_cvt_pk_bf16_f32 %0, %1, %2" : "=v"(r) : "v"(lo), "v"(hi)); return r; }
; __device__ __forceinline__ void cvt_store(const CvtJob& j, int tid, const f32x4 (&v)[8], const float (&gk)[8], LAS unsigned char* lds) {
;     LAS bf16_t* T = (LAS bf16_t*)lds;
;     {
;         const int nq = tid & 31, kk = tid >> 5;
; #pragma unroll
;         for (int i = 0; i < 8; ++i) {
;             const int k = kk + 16 * i;
; #pragma unroll
;             for (int jj = 0; jj < 4; ++jj) { const unsigned w = cvt_pk_bf16(v[i][jj] * gk[i], 0.f); T[(jj * 32 + nq) * 130 + k] = (bf16_t)(w & 0xffffu); }
;         }
;     }
;     __syncthreads();
;     {
;         const int n = tid >> 2, kc = tid & 3, rs_ = (n & 3) * 32 + (n >> 2);
;         const LAS unsigned* T32 = (const LAS unsigned*)lds;
;         bf16_t* d = j.dst + (size_t)(j.n0 + n) * j.K + j.k0 + kc * 32;
; #pragma unroll
;         for (int h2 = 0; h2 < 4; ++h2) {
;             u32x4 w;
;             w.x = T32[rs_ * 65 + kc * 16 + h2 * 4 + 0]; w.y = T32[rs_ * 65 + kc * 16 + h2 * 4 + 1]; w.z = T32[rs_ * 65 + kc * 16 + h2 * 4 + 2]; w.w = T32[rs_ * 65 + kc * 16 + h2 * 4 + 3];
;             *(u32x4*)(d + h2 * 8) = w;
;         }
;     }
;     __syncthreads();
; }
; template <bool PREPMAP>
; __device__ __forceinline__ void convert_jobs(const Params& p, int job0, int job_end, int stride, LAS unsigned char* lds) {
;     ...
;         cvt_store(cur, tid, v, gk, lds);
;         if (!more) break;
; #pragma unroll
;         for (int i = 0; i < 8; ++i) { v[i] = v2[i]; gk[i] = gk2[i]; }
;         cur = nxt; job = nj;
.LBB0_194:
	v_mul_f32_e32 v73, v75, v2
	v_cvt_pk_bf16_f32 v73, v73, v71
	ds_write_b16 v92, v73
	v_mul_f32_e32 v73, v75, v3
	v_cvt_pk_bf16_f32 v73, v73, v71
	ds_write_b16 v92, v73 offset:8320
	v_mul_f32_e32 v73, v75, v4
	v_cvt_pk_bf16_f32 v73, v73, v71
	ds_write_b16 v92, v73 offset:16640
	v_mul_f32_e32 v73, v75, v5
	v_cvt_pk_bf16_f32 v73, v73, v71
	ds_write_b16 v92, v73 offset:24960
	v_mul_f32_e32 v73, v77, v6
	v_cvt_pk_bf16_f32 v73, v73, v71
	ds_write_b16 v92, v73 offset:32
	v_mul_f32_e32 v73, v77, v7
	v_cvt_pk_bf16_f32 v73, v73, v71
	ds_write_b16 v92, v73 offset:8352
	v_mul_f32_e32 v73, v77, v8
	v_cvt_pk_bf16_f32 v73, v73, v71
	ds_write_b16 v92, v73 offset:16672
	v_mul_f32_e32 v73, v77, v9
	v_cvt_pk_bf16_f32 v73, v73, v71
	ds_write_b16 v92, v73 offset:24992
	v_mul_f32_e32 v73, v78, v10
	v_cvt_pk_bf16_f32 v73, v73, v71
	ds_write_b16 v92, v73 offset:64
	v_mul_f32_e32 v73, v78, v11
	v_cvt_pk_bf16_f32 v73, v73, v71
	ds_write_b16 v92, v73 offset:8384
	v_mul_f32_e32 v73, v78, v12
	v_cvt_pk_bf16_f32 v73, v73, v71
	ds_write_b16 v92, v73 offset:16704
	v_mul_f32_e32 v73, v78, v13
	v_cvt_pk_bf16_f32 v73, v73, v71
	ds_write_b16 v92, v73 offset:25024
	v_mul_f32_e32 v73, v80, v14
	v_cvt_pk_bf16_f32 v73, v73, v71
	ds_write_b16 v92, v73 offset:96
	v_mul_f32_e32 v73, v80, v15
	v_cvt_pk_bf16_f32 v73, v73, v71
	ds_write_b16 v92, v73 offset:8416
	v_mul_f32_e32 v73, v80, v16
	v_cvt_pk_bf16_f32 v73, v73, v71
	ds_write_b16 v92, v73 offset:16736
	v_mul_f32_e32 v73, v80, v17
	v_cvt_pk_bf16_f32 v73, v73, v71
	ds_write_b16 v92, v73 offset:25056
	v_mul_f32_e32 v73, v82, v18
	v_cvt_pk_bf16_f32 v73, v73, v71
	ds_write_b16 v92, v73 offset:128
	v_mul_f32_e32 v73, v82, v19
	v_cvt_pk_bf16_f32 v73, v73, v71
	ds_write_b16 v92, v73 offset:8448
	v_mul_f32_e32 v73, v82, v20
	v_cvt_pk_bf16_f32 v73, v73, v71
	ds_write_b16 v92, v73 offset:16768
	v_mul_f32_e32 v73, v82, v21
	v_cvt_pk_bf16_f32 v73, v73, v71
	ds_write_b16 v92, v73 offset:25088
	v_mul_f32_e32 v73, v84, v22
	v_cvt_pk_bf16_f32 v73, v73, v71
	ds_write_b16 v92, v73 offset:160
	v_mul_f32_e32 v73, v84, v23
	v_cvt_pk_bf16_f32 v73, v73, v71
	ds_write_b16 v92, v73 offset:8480
	v_mul_f32_e32 v73, v84, v24
	v_cvt_pk_bf16_f32 v73, v73, v71
	ds_write_b16 v92, v73 offset:16800
	v_mul_f32_e32 v73, v84, v25
	v_cvt_pk_bf16_f32 v73, v73, v71
	ds_write_b16 v92, v73 offset:25120
	v_mul_f32_e32 v73, v86, v26
	v_cvt_pk_bf16_f32 v73, v73, v71
	ds_write_b16 v92, v73 offset:192
	v_mul_f32_e32 v73, v86, v27
	v_cvt_pk_bf16_f32 v73, v73, v71
	ds_write_b16 v92, v73 offset:8512
	v_mul_f32_e32 v73, v86, v28
	v_cvt_pk_bf16_f32 v73, v73, v71
	ds_write_b16 v92, v73 offset:16832
	v_mul_f32_e32 v73, v86, v29
	v_cvt_pk_bf16_f32 v73, v73, v71
	ds_write_b16 v92, v73 offset:25152
	v_mul_f32_e32 v73, v88, v30
	v_cvt_pk_bf16_f32 v73, v73, v71
	ds_write_b16 v92, v73 offset:224
	v_mul_f32_e32 v73, v88, v31
	v_cvt_pk_bf16_f32 v73, v73, v71
	ds_write_b16 v92, v73 offset:8544
	v_mul_f32_e32 v73, v88, v32
	v_cvt_pk_bf16_f32 v73, v73, v71
	ds_write_b16 v92, v73 offset:16864
	v_mul_f32_e32 v73, v88, v33
	v_cvt_pk_bf16_f32 v73, v73, v71
	ds_write_b16 v92, v73 offset:25184
	v_add_u32_e32 v73, s33, v91
	v_mad_u64_u32 v[102:103], s[4:5], s25, v73, 0
	v_ashrrev_i32_e32 v101, 31, v73
	v_mov_b32_e32 v104, v103
	v_mad_u64_u32 v[104:105], s[4:5], s25, v101, v[104:105]
	v_mov_b32_e32 v103, v104
	v_lshl_add_u64 v[102:103], v[102:103], 1, s[34:35]
	s_ashr_i32 s37, s36, 31
	s_waitcnt lgkmcnt(0)
	s_barrier
	v_lshl_add_u64 v[118:119], s[36:37], 1, v[102:103]
	ds_read2_b32 v[102:103], v93 offset1:1
	ds_read2_b32 v[104:105], v93 offset0:2 offset1:3
	ds_read2_b32 v[106:107], v93 offset0:4 offset1:5
	ds_read2_b32 v[108:109], v93 offset0:6 offset1:7
	ds_read2_b32 v[110:111], v93 offset0:8 offset1:9
	ds_read2_b32 v[112:113], v93 offset0:10 offset1:11
	ds_read2_b32 v[114:115], v93 offset0:12 offset1:13
	ds_read2_b32 v[116:117], v93 offset0:14 offset1:15
	v_mov_b32_e32 v73, v71
	v_lshl_add_u64 v[118:119], v[118:119], 0, v[72:73]
	s_andn2_b64 vcc, exec, s[46:47]
	s_waitcnt lgkmcnt(6)
	global_store_dwordx4 v[118:119], v[102:105], off
	s_waitcnt lgkmcnt(4)
	global_store_dwordx4 v[118:119], v[106:109], off offset:16
	s_waitcnt lgkmcnt(2)
	global_store_dwordx4 v[118:119], v[110:113], off offset:32
	s_waitcnt lgkmcnt(0)
	global_store_dwordx4 v[118:119], v[114:117], off offset:48
	s_barrier
	s_cbranch_vccnz .LBB0_105
	s_waitcnt vmcnt(0)
	v_mov_b32_e32 v88, v70
	v_mov_b32_e32 v86, v100
	v_mov_b32_e32 v84, v99
	v_mov_b32_e32 v82, v98
	v_mov_b32_e32 v80, v97
	v_mov_b32_e32 v78, v96
	v_mov_b32_e32 v77, v95
	v_mov_b32_e32 v75, v94
	s_mov_b32 s33, s67
	s_mov_b32 s36, s56
	s_mov_b32 s25, s66
	s_mov_b64 s[34:35], s[48:49]
	s_mov_b32 s24, s65
	v_mov_b32_e32 v2, v34
	v_mov_b32_e32 v3, v35
	v_mov_b32_e32 v4, v36
	v_mov_b32_e32 v5, v37
	v_mov_b32_e32 v6, v38
	v_mov_b32_e32 v7, v39
	v_mov_b32_e32 v8, v40
	v_mov_b32_e32 v9, v41
	v_mov_b32_e32 v10, v42
	v_mov_b32_e32 v11, v43
	v_mov_b32_e32 v12, v44
	v_mov_b32_e32 v13, v45
	v_mov_b32_e32 v14, v46
	v_mov_b32_e32 v15, v47
	v_mov_b32_e32 v16, v48
	v_mov_b32_e32 v17, v49
	v_mov_b32_e32 v18, v50
	v_mov_b32_e32 v19, v51
	v_mov_b32_e32 v20, v52
	v_mov_b32_e32 v21, v53
	v_mov_b32_e32 v22, v54
	v_mov_b32_e32 v23, v55
	v_mov_b32_e32 v24, v56
	v_mov_b32_e32 v25, v57
	v_mov_b32_e32 v26, v58
	v_mov_b32_e32 v27, v59
	v_mov_b32_e32 v28, v60
	v_mov_b32_e32 v29, v61
	v_mov_b32_e32 v30, v62
	v_mov_b32_e32 v31, v63
	v_mov_b32_e32 v32, v64
	v_mov_b32_e32 v33, v65
	s_branch .LBB0_105

; #define LAS __attribute__((address_space(3)))
; __device__ __forceinline__ unsigned cvt_pk_bf16(float lo, float hi) { unsigned r; asm volatile("v_cvt_pk_bf16_f32 %0, %1, %2" : "=v"(r) : "v"(lo), "v"(hi)); return r; }
; __device__ __forceinline__ void cvt_store(const CvtJob& j, int tid, const f32x4 (&v)[8], const float (&gk)[8], LAS unsigned char* lds) {
;     LAS bf16_t* T = (LAS bf16_t*)lds;
;     {
;         const int nq = tid & 31, kk = tid >> 5;
; #pragma unroll
;         for (int i = 0; i < 8; ++i) {
;             const int k = kk + 16 * i;
; #pragma unroll
;             for (int jj = 0; jj < 4; ++jj) { const unsigned w = cvt_pk_bf16(v[i][jj] * gk[i], 0.f); T[(jj * 32 + nq) * 130 + k] = (bf16_t)(w & 0xffffu); }
;         }
;     }
;     __syncthreads();
;     {
;         const int n = tid >> 2, kc = tid & 3, rs_ = (n & 3) * 32 + (n >> 2);
;         const LAS unsigned* T32 = (const LAS unsigned*)lds;
;         bf16_t* d = j.dst + (size_t)(j.n0 + n) * j.K + j.k0 + kc * 32;
; template <bool PREPMAP>
; __device__ __forceinline__ void convert_jobs(const Params& p, int job0, int job_end, int stride, LAS unsigned char* lds) {
;     ...
;     for (;;) {
;         const int nj = job + stride; const bool more = nj < job_end;
;         CvtJob nxt = cur; f32x4 v2[8]; float gk2[8];
;         if (more) { nxt = cvt_decode(p, cvt_map<PREPMAP>(nj)); cvt_load(nxt, tid, v2, gk2); }
.LBB0_497:
	v_and_b32_e32 v0, 31, v36
	v_ashrrev_i32_e32 v90, 2, v36
	v_mul_u32_u24_e32 v35, 0x104, v0
	v_lshlrev_b32_e32 v0, 5, v90
	v_readlane_b32 s0, v253, 50
	v_bfe_u32 v88, v37, 5, 2
	v_and_b32_e32 v89, 28, v37
	v_and_b32_e32 v37, 3, v36
	v_and_b32_e32 v0, 0x60, v0
	v_ashrrev_i32_e32 v36, 4, v36
	s_add_i32 s29, s0, s3
	v_add_u32_e32 v36, v0, v36
	s_movk_i32 s0, 0x104
	v_mul_lo_u32 v36, v36, s0
	v_lshl_add_u32 v34, v66, 1, 0
	v_lshlrev_b32_e32 v0, 5, v37
	v_add_u32_e32 v36, 0, v36
	v_lshlrev_b32_e32 v37, 6, v37
	v_add_u32_e32 v91, v34, v35
	v_lshlrev_b32_e32 v68, 1, v0
	v_add_u32_e32 v92, v36, v37
	s_waitcnt vmcnt(0)
	s_branch .LBB0_499

; #define LAS __attribute__((address_space(3)))
; __device__ __forceinline__ unsigned cvt_pk_bf16(float lo, float hi) { unsigned r; asm volatile("v_cvt_pk_bf16_f32 %0, %1, %2" : "=v"(r) : "v"(lo), "v"(hi)); return r; }
; __device__ __forceinline__ void cvt_store(const CvtJob& j, int tid, const f32x4 (&v)[8], const float (&gk)[8], LAS unsigned char* lds) {
;     LAS bf16_t* T = (LAS bf16_t*)lds;
;     {
;         const int nq = tid & 31, kk = tid >> 5;
; #pragma unroll
;         for (int i = 0; i < 8; ++i) {
;             const int k = kk + 16 * i;
; #pragma unroll
;             for (int jj = 0; jj < 4; ++jj) { const unsigned w = cvt_pk_bf16(v[i][jj] * gk[i], 0.f); T[(jj * 32 + nq) * 130 + k] = (bf16_t)(w & 0xffffu); }
;         }
;     }
;     __syncthreads();
;     {
;         const int n = tid >> 2, kc = tid & 3, rs_ = (n & 3) * 32 + (n >> 2);
;         const LAS unsigned* T32 = (const LAS unsigned*)lds;
;         bf16_t* d = j.dst + (size_t)(j.n0 + n) * j.K + j.k0 + kc * 32;
; #pragma unroll
;         for (int h2 = 0; h2 < 4; ++h2) {
;             u32x4 w;
;             w.x = T32[rs_ * 65 + kc * 16 + h2 * 4 + 0]; w.y = T32[rs_ * 65 + kc * 16 + h2 * 4 + 1]; w.z = T32[rs_ * 65 + kc * 16 + h2 * 4 + 2]; w.w = T32[rs_ * 65 + kc * 16 + h2 * 4 + 3];
;             *(u32x4*)(d + h2 * 8) = w;
;         }
;     }
;     __syncthreads();
; }
; template <bool PREPMAP>
; __device__ __forceinline__ void convert_jobs(const Params& p, int job0, int job_end, int stride, LAS unsigned char* lds) {
;     ...
;         cvt_store(cur, tid, v, gk, lds);
;         if (!more) break;
; #pragma unroll
;         for (int i = 0; i < 8; ++i) { v[i] = v2[i]; gk[i] = gk2[i]; }
;         cur = nxt; job = nj;
.LBB0_584:
	v_mul_f32_e32 v69, v74, v2
	v_cvt_pk_bf16_f32 v69, v69, v1
	ds_write_b16 v91, v69
	v_mul_f32_e32 v69, v74, v3
	v_cvt_pk_bf16_f32 v69, v69, v1
	ds_write_b16 v91, v69 offset:8320
	v_mul_f32_e32 v69, v74, v4
	v_cvt_pk_bf16_f32 v69, v69, v1
	ds_write_b16 v91, v69 offset:16640
	v_mul_f32_e32 v69, v74, v5
	v_cvt_pk_bf16_f32 v69, v69, v1
	ds_write_b16 v91, v69 offset:24960
	v_mul_f32_e32 v69, v76, v6
	v_cvt_pk_bf16_f32 v69, v69, v1
	ds_write_b16 v91, v69 offset:32
	v_mul_f32_e32 v69, v76, v7
	v_cvt_pk_bf16_f32 v69, v69, v1
	ds_write_b16 v91, v69 offset:8352
	v_mul_f32_e32 v69, v76, v8
	v_cvt_pk_bf16_f32 v69, v69, v1
	ds_write_b16 v91, v69 offset:16672
	v_mul_f32_e32 v69, v76, v9
	v_cvt_pk_bf16_f32 v69, v69, v1
	ds_write_b16 v91, v69 offset:24992
	v_mul_f32_e32 v69, v77, v10
	v_cvt_pk_bf16_f32 v69, v69, v1
	ds_write_b16 v91, v69 offset:64
	v_mul_f32_e32 v69, v77, v11
	v_cvt_pk_bf16_f32 v69, v69, v1
	ds_write_b16 v91, v69 offset:8384
	v_mul_f32_e32 v69, v77, v12
	v_cvt_pk_bf16_f32 v69, v69, v1
	ds_write_b16 v91, v69 offset:16704
	v_mul_f32_e32 v69, v77, v13
	v_cvt_pk_bf16_f32 v69, v69, v1
	ds_write_b16 v91, v69 offset:25024
	v_mul_f32_e32 v69, v79, v14
	v_cvt_pk_bf16_f32 v69, v69, v1
	ds_write_b16 v91, v69 offset:96
	v_mul_f32_e32 v69, v79, v15
	v_cvt_pk_bf16_f32 v69, v69, v1
	ds_write_b16 v91, v69 offset:8416
	v_mul_f32_e32 v69, v79, v16
	v_cvt_pk_bf16_f32 v69, v69, v1
	ds_write_b16 v91, v69 offset:16736
	v_mul_f32_e32 v69, v79, v17
	v_cvt_pk_bf16_f32 v69, v69, v1
	ds_write_b16 v91, v69 offset:25056
	v_mul_f32_e32 v69, v81, v18
	v_cvt_pk_bf16_f32 v69, v69, v1
	ds_write_b16 v91, v69 offset:128
	v_mul_f32_e32 v69, v81, v19
	v_cvt_pk_bf16_f32 v69, v69, v1
	ds_write_b16 v91, v69 offset:8448
	v_mul_f32_e32 v69, v81, v20
	v_cvt_pk_bf16_f32 v69, v69, v1
	ds_write_b16 v91, v69 offset:16768
	v_mul_f32_e32 v69, v81, v21
	v_cvt_pk_bf16_f32 v69, v69, v1
	ds_write_b16 v91, v69 offset:25088
	v_mul_f32_e32 v69, v83, v22
	v_cvt_pk_bf16_f32 v69, v69, v1
	ds_write_b16 v91, v69 offset:160
	v_mul_f32_e32 v69, v83, v23
	v_cvt_pk_bf16_f32 v69, v69, v1
	ds_write_b16 v91, v69 offset:8480
	v_mul_f32_e32 v69, v83, v24
	v_cvt_pk_bf16_f32 v69, v69, v1
	ds_write_b16 v91, v69 offset:16800
	v_mul_f32_e32 v69, v83, v25
	v_cvt_pk_bf16_f32 v69, v69, v1
	ds_write_b16 v91, v69 offset:25120
	v_mul_f32_e32 v69, v85, v26
	v_cvt_pk_bf16_f32 v69, v69, v1
	ds_write_b16 v91, v69 offset:192
	v_mul_f32_e32 v69, v85, v27
	v_cvt_pk_bf16_f32 v69, v69, v1
	ds_write_b16 v91, v69 offset:8512
	v_mul_f32_e32 v69, v85, v28
	v_cvt_pk_bf16_f32 v69, v69, v1
	ds_write_b16 v91, v69 offset:16832
	v_mul_f32_e32 v69, v85, v29
	v_cvt_pk_bf16_f32 v69, v69, v1
	ds_write_b16 v91, v69 offset:25152
	v_mul_f32_e32 v69, v87, v30
	v_cvt_pk_bf16_f32 v69, v69, v1
	ds_write_b16 v91, v69 offset:224
	v_mul_f32_e32 v69, v87, v31
	v_cvt_pk_bf16_f32 v69, v69, v1
	ds_write_b16 v91, v69 offset:8544
	v_mul_f32_e32 v69, v87, v32
	v_cvt_pk_bf16_f32 v69, v69, v1
	ds_write_b16 v91, v69 offset:16864
	v_mul_f32_e32 v69, v87, v33
	v_cvt_pk_bf16_f32 v69, v69, v1
	ds_write_b16 v91, v69 offset:25184
	v_add_u32_e32 v69, s28, v90
	v_mad_u64_u32 v[70:71], s[0:1], s24, v69, 0
	v_ashrrev_i32_e32 v101, 31, v69
	v_mov_b32_e32 v100, v71
	v_mad_u64_u32 v[100:101], s[0:1], s24, v101, v[100:101]
	s_waitcnt lgkmcnt(0)
	s_barrier
	v_mov_b32_e32 v71, v100
	ds_read2_b32 v[100:101], v92 offset1:1
	ds_read2_b32 v[102:103], v92 offset0:2 offset1:3
	v_lshl_add_u64 v[70:71], v[70:71], 1, s[4:5]
	s_ashr_i32 s9, s8, 31
	v_lshl_add_u64 v[70:71], s[8:9], 1, v[70:71]
	v_mov_b32_e32 v69, v1
	v_lshl_add_u64 v[70:71], v[70:71], 0, v[68:69]
	s_waitcnt lgkmcnt(0)
	global_store_dwordx4 v[70:71], v[100:103], off
	ds_read2_b32 v[100:101], v92 offset0:4 offset1:5
	ds_read2_b32 v[102:103], v92 offset0:6 offset1:7
	s_andn2_b64 vcc, exec, s[16:17]
	s_waitcnt lgkmcnt(0)
	global_store_dwordx4 v[70:71], v[100:103], off offset:16
	ds_read2_b32 v[100:101], v92 offset0:8 offset1:9
	ds_read2_b32 v[102:103], v92 offset0:10 offset1:11
	s_waitcnt lgkmcnt(0)
	global_store_dwordx4 v[70:71], v[100:103], off offset:32
	ds_read2_b32 v[100:101], v92 offset0:12 offset1:13
	ds_read2_b32 v[102:103], v92 offset0:14 offset1:15
	s_waitcnt lgkmcnt(0)
	global_store_dwordx4 v[70:71], v[100:103], off offset:48
	s_barrier
	s_cbranch_vccnz .LBB0_498
	s_waitcnt vmcnt(0)
	v_mov_b32_e32 v87, v0
	v_mov_b32_e32 v85, v99
	v_mov_b32_e32 v83, v98
	v_mov_b32_e32 v81, v97
	v_mov_b32_e32 v79, v96
	v_mov_b32_e32 v77, v95
	v_mov_b32_e32 v76, v94
	v_mov_b32_e32 v74, v93
	s_mov_b32 s28, s7
	s_mov_b32 s8, s42
	s_mov_b32 s24, s6
	s_mov_b64 s[4:5], s[18:19]
	s_mov_b32 s14, s3
	v_mov_b32_e32 v2, v34
	v_mov_b32_e32 v3, v35
	v_mov_b32_e32 v4, v36
	v_mov_b32_e32 v5, v37
	v_mov_b32_e32 v6, v38
	v_mov_b32_e32 v7, v39
	v_mov_b32_e32 v8, v40
	v_mov_b32_e32 v9, v41
	v_mov_b32_e32 v10, v42
	v_mov_b32_e32 v11, v43
	v_mov_b32_e32 v12, v44
	v_mov_b32_e32 v13, v45
	v_mov_b32_e32 v14, v46
	v_mov_b32_e32 v15, v47
	v_mov_b32_e32 v16, v48
	v_mov_b32_e32 v17, v49
	v_mov_b32_e32 v18, v50
	v_mov_b32_e32 v19, v51
	v_mov_b32_e32 v20, v52
	v_mov_b32_e32 v21, v53
	v_mov_b32_e32 v22, v54
	v_mov_b32_e32 v23, v55
	v_mov_b32_e32 v24, v56
	v_mov_b32_e32 v25, v57
	v_mov_b32_e32 v26, v58
	v_mov_b32_e32 v27, v59
	v_mov_b32_e32 v28, v60
	v_mov_b32_e32 v29, v61
	v_mov_b32_e32 v30, v62
	v_mov_b32_e32 v31, v63
	v_mov_b32_e32 v32, v64
	v_mov_b32_e32 v33, v65
	s_branch .LBB0_498

; #define LAS __attribute__((address_space(3)))
; __device__ __forceinline__ unsigned cvt_pk_bf16(float lo, float hi) { unsigned r; asm volatile("v_cvt_pk_bf16_f32 %0, %1, %2" : "=v"(r) : "v"(lo), "v"(hi)); return r; }
; __device__ __forceinline__ void cvt_store(const CvtJob& j, int tid, const f32x4 (&v)[8], const float (&gk)[8], LAS unsigned char* lds) {
;     LAS bf16_t* T = (LAS bf16_t*)lds;
;     {
;         const int nq = tid & 31, kk = tid >> 5;
; #pragma unroll
;         for (int i = 0; i < 8; ++i) {
;             const int k = kk + 16 * i;
; #pragma unroll
;             for (int jj = 0; jj < 4; ++jj) { const unsigned w = cvt_pk_bf16(v[i][jj] * gk[i], 0.f); T[(jj * 32 + nq) * 130 + k] = (bf16_t)(w & 0xffffu); }
;         }
;     }
;     __syncthreads();
;     {
;         const int n = tid >> 2, kc = tid & 3, rs_ = (n & 3) * 32 + (n >> 2);
;         const LAS unsigned* T32 = (const LAS unsigned*)lds;
;         bf16_t* d = j.dst + (size_t)(j.n0 + n) * j.K + j.k0 + kc * 32;
; template <bool PREPMAP>
; __device__ __forceinline__ void convert_jobs(const Params& p, int job0, int job_end, int stride, LAS unsigned char* lds) {
;     ...
;     for (;;) {
;         const int nj = job + stride; const bool more = nj < job_end;
;         CvtJob nxt = cur; f32x4 v2[8]; float gk2[8];
;         if (more) { nxt = cvt_decode(p, cvt_map<PREPMAP>(nj)); cvt_load(nxt, tid, v2, gk2); }
.LBB0_673:
	v_and_b32_e32 v0, 31, v36
	v_ashrrev_i32_e32 v90, 2, v36
	v_mul_u32_u24_e32 v35, 0x104, v0
	v_lshlrev_b32_e32 v0, 5, v90
	v_bfe_u32 v88, v37, 5, 2
	v_and_b32_e32 v89, 28, v37
	v_and_b32_e32 v37, 3, v36
	v_and_b32_e32 v0, 0x60, v0
	v_ashrrev_i32_e32 v36, 4, v36
	v_add_u32_e32 v36, v0, v36
	s_movk_i32 s0, 0x104
	v_mul_lo_u32 v36, v36, s0
	v_lshl_add_u32 v34, v66, 1, 0
	v_lshlrev_b32_e32 v0, 5, v37
	v_add_u32_e32 v36, 0, v36
	v_lshlrev_b32_e32 v37, 6, v37
	v_add_u32_e32 v91, v34, v35
	v_lshlrev_b32_e32 v68, 1, v0
	v_add_u32_e32 v92, v36, v37
	s_waitcnt vmcnt(0)
	s_branch .LBB0_675

; #define LAS __attribute__((address_space(3)))
; __device__ __forceinline__ unsigned cvt_pk_bf16(float lo, float hi) { unsigned r; asm volatile("v_cvt_pk_bf16_f32 %0, %1, %2" : "=v"(r) : "v"(lo), "v"(hi)); return r; }
; __device__ __forceinline__ void cvt_store(const CvtJob& j, int tid, const f32x4 (&v)[8], const float (&gk)[8], LAS unsigned char* lds) {
;     LAS bf16_t* T = (LAS bf16_t*)lds;
;     {
;         const int nq = tid & 31, kk = tid >> 5;
; #pragma unroll
;         for (int i = 0; i < 8; ++i) {
;             const int k = kk + 16 * i;
; #pragma unroll
;             for (int jj = 0; jj < 4; ++jj) { const unsigned w = cvt_pk_bf16(v[i][jj] * gk[i], 0.f); T[(jj * 32 + nq) * 130 + k] = (bf16_t)(w & 0xffffu); }
;         }
;     }
;     __syncthreads();
;     {
;         const int n = tid >> 2, kc = tid & 3, rs_ = (n & 3) * 32 + (n >> 2);
;         const LAS unsigned* T32 = (const LAS unsigned*)lds;
;         bf16_t* d = j.dst + (size_t)(j.n0 + n) * j.K + j.k0 + kc * 32;
; template <bool PREPMAP>
; __device__ __forceinline__ void convert_jobs(const Params& p, int job0, int job_end, int stride, LAS unsigned char* lds) {
;     ...
;     for (;;) {
;         const int nj = job + stride; const bool more = nj < job_end;
;         CvtJob nxt = cur; f32x4 v2[8]; float gk2[8];
;         if (more) { nxt = cvt_decode(p, cvt_map<PREPMAP>(nj)); cvt_load(nxt, tid, v2, gk2); }
.LBB0_1144:
	v_and_b32_e32 v0, 31, v36
	v_ashrrev_i32_e32 v90, 2, v36
	v_mul_u32_u24_e32 v35, 0x104, v0
	v_lshlrev_b32_e32 v0, 5, v90
	v_readlane_b32 s0, v253, 63
	v_bfe_u32 v88, v37, 5, 2
	v_and_b32_e32 v89, 28, v37
	v_and_b32_e32 v37, 3, v36
	v_and_b32_e32 v0, 0x60, v0
	v_ashrrev_i32_e32 v36, 4, v36
	s_add_i32 s24, s0, s3
	v_add_u32_e32 v36, v0, v36
	s_movk_i32 s0, 0x104
	v_mul_lo_u32 v36, v36, s0
	v_lshl_add_u32 v34, v66, 1, 0
	v_lshlrev_b32_e32 v0, 5, v37
	v_add_u32_e32 v36, 0, v36
	v_lshlrev_b32_e32 v37, 6, v37
	v_add_u32_e32 v91, v34, v35
	v_lshlrev_b32_e32 v68, 1, v0
	v_add_u32_e32 v92, v36, v37
	s_waitcnt vmcnt(0)
	s_branch .LBB0_1146

; #define LAS __attribute__((address_space(3)))
; __device__ __forceinline__ unsigned cvt_pk_bf16(float lo, float hi) { unsigned r; asm volatile("v_cvt_pk_bf16_f32 %0, %1, %2" : "=v"(r) : "v"(lo), "v"(hi)); return r; }
; __device__ __forceinline__ void cvt_store(const CvtJob& j, int tid, const f32x4 (&v)[8], const float (&gk)[8], LAS unsigned char* lds) {
;     LAS bf16_t* T = (LAS bf16_t*)lds;
;     {
;         const int nq = tid & 31, kk = tid >> 5;
; #pragma unroll
;         for (int i = 0; i < 8; ++i) {
;             const int k = kk + 16 * i;
; #pragma unroll
;             for (int jj = 0; jj < 4; ++jj) { const unsigned w = cvt_pk_bf16(v[i][jj] * gk[i], 0.f); T[(jj * 32 + nq) * 130 + k] = (bf16_t)(w & 0xffffu); }
;         }
;     }
;     __syncthreads();
;     {
;         const int n = tid >> 2, kc = tid & 3, rs_ = (n & 3) * 32 + (n >> 2);
;         const LAS unsigned* T32 = (const LAS unsigned*)lds;
;         bf16_t* d = j.dst + (size_t)(j.n0 + n) * j.K + j.k0 + kc * 32;
; #pragma unroll
;         for (int h2 = 0; h2 < 4; ++h2) {
;             u32x4 w;
;             w.x = T32[rs_ * 65 + kc * 16 + h2 * 4 + 0]; w.y = T32[rs_ * 65 + kc * 16 + h2 * 4 + 1]; w.z = T32[rs_ * 65 + kc * 16 + h2 * 4 + 2]; w.w = T32[rs_ * 65 + kc * 16 + h2 * 4 + 3];
;             *(u32x4*)(d + h2 * 8) = w;
;         }
;     }
;     __syncthreads();
; }
; template <bool PREPMAP>
; __device__ __forceinline__ void convert_jobs(const Params& p, int job0, int job_end, int stride, LAS unsigned char* lds) {
;     ...
;         cvt_store(cur, tid, v, gk, lds);
;         if (!more) break;
; #pragma unroll
;         for (int i = 0; i < 8; ++i) { v[i] = v2[i]; gk[i] = gk2[i]; }
;         cur = nxt; job = nj;
.LBB0_1231:
	v_mul_f32_e32 v69, v74, v2
	v_cvt_pk_bf16_f32 v69, v69, v1
	ds_write_b16 v91, v69
	v_mul_f32_e32 v69, v74, v3
	v_cvt_pk_bf16_f32 v69, v69, v1
	ds_write_b16 v91, v69 offset:8320
	v_mul_f32_e32 v69, v74, v4
	v_cvt_pk_bf16_f32 v69, v69, v1
	ds_write_b16 v91, v69 offset:16640
	v_mul_f32_e32 v69, v74, v5
	v_cvt_pk_bf16_f32 v69, v69, v1
	ds_write_b16 v91, v69 offset:24960
	v_mul_f32_e32 v69, v76, v6
	v_cvt_pk_bf16_f32 v69, v69, v1
	ds_write_b16 v91, v69 offset:32
	v_mul_f32_e32 v69, v76, v7
	v_cvt_pk_bf16_f32 v69, v69, v1
	ds_write_b16 v91, v69 offset:8352
	v_mul_f32_e32 v69, v76, v8
	v_cvt_pk_bf16_f32 v69, v69, v1
	ds_write_b16 v91, v69 offset:16672
	v_mul_f32_e32 v69, v76, v9
	v_cvt_pk_bf16_f32 v69, v69, v1
	ds_write_b16 v91, v69 offset:24992
	v_mul_f32_e32 v69, v77, v10
	v_cvt_pk_bf16_f32 v69, v69, v1
	ds_write_b16 v91, v69 offset:64
	v_mul_f32_e32 v69, v77, v11
	v_cvt_pk_bf16_f32 v69, v69, v1
	ds_write_b16 v91, v69 offset:8384
	v_mul_f32_e32 v69, v77, v12
	v_cvt_pk_bf16_f32 v69, v69, v1
	ds_write_b16 v91, v69 offset:16704
	v_mul_f32_e32 v69, v77, v13
	v_cvt_pk_bf16_f32 v69, v69, v1
	ds_write_b16 v91, v69 offset:25024
	v_mul_f32_e32 v69, v79, v14
	v_cvt_pk_bf16_f32 v69, v69, v1
	ds_write_b16 v91, v69 offset:96
	v_mul_f32_e32 v69, v79, v15
	v_cvt_pk_bf16_f32 v69, v69, v1
	ds_write_b16 v91, v69 offset:8416
	v_mul_f32_e32 v69, v79, v16
	v_cvt_pk_bf16_f32 v69, v69, v1
	ds_write_b16 v91, v69 offset:16736
	v_mul_f32_e32 v69, v79, v17
	v_cvt_pk_bf16_f32 v69, v69, v1
	ds_write_b16 v91, v69 offset:25056
	v_mul_f32_e32 v69, v81, v18
	v_cvt_pk_bf16_f32 v69, v69, v1
	ds_write_b16 v91, v69 offset:128
	v_mul_f32_e32 v69, v81, v19
	v_cvt_pk_bf16_f32 v69, v69, v1
	ds_write_b16 v91, v69 offset:8448
	v_mul_f32_e32 v69, v81, v20
	v_cvt_pk_bf16_f32 v69, v69, v1
	ds_write_b16 v91, v69 offset:16768
	v_mul_f32_e32 v69, v81, v21
	v_cvt_pk_bf16_f32 v69, v69, v1
	ds_write_b16 v91, v69 offset:25088
	v_mul_f32_e32 v69, v83, v22
	v_cvt_pk_bf16_f32 v69, v69, v1
	ds_write_b16 v91, v69 offset:160
	v_mul_f32_e32 v69, v83, v23
	v_cvt_pk_bf16_f32 v69, v69, v1
	ds_write_b16 v91, v69 offset:8480
	v_mul_f32_e32 v69, v83, v24
	v_cvt_pk_bf16_f32 v69, v69, v1
	ds_write_b16 v91, v69 offset:16800
	v_mul_f32_e32 v69, v83, v25
	v_cvt_pk_bf16_f32 v69, v69, v1
	ds_write_b16 v91, v69 offset:25120
	v_mul_f32_e32 v69, v85, v26
	v_cvt_pk_bf16_f32 v69, v69, v1
	ds_write_b16 v91, v69 offset:192
	v_mul_f32_e32 v69, v85, v27
	v_cvt_pk_bf16_f32 v69, v69, v1
	ds_write_b16 v91, v69 offset:8512
	v_mul_f32_e32 v69, v85, v28
	v_cvt_pk_bf16_f32 v69, v69, v1
	ds_write_b16 v91, v69 offset:16832
	v_mul_f32_e32 v69, v85, v29
	v_cvt_pk_bf16_f32 v69, v69, v1
	ds_write_b16 v91, v69 offset:25152
	v_mul_f32_e32 v69, v87, v30
	v_cvt_pk_bf16_f32 v69, v69, v1
	ds_write_b16 v91, v69 offset:224
	v_mul_f32_e32 v69, v87, v31
	v_cvt_pk_bf16_f32 v69, v69, v1
	ds_write_b16 v91, v69 offset:8544
	v_mul_f32_e32 v69, v87, v32
	v_cvt_pk_bf16_f32 v69, v69, v1
	ds_write_b16 v91, v69 offset:16864
	v_mul_f32_e32 v69, v87, v33
	v_cvt_pk_bf16_f32 v69, v69, v1
	ds_write_b16 v91, v69 offset:25184
	v_add_u32_e32 v69, s14, v90
	v_mad_u64_u32 v[70:71], s[0:1], s13, v69, 0
	v_ashrrev_i32_e32 v101, 31, v69
	v_mov_b32_e32 v100, v71
	v_mad_u64_u32 v[100:101], s[0:1], s13, v101, v[100:101]
	s_waitcnt lgkmcnt(0)
	s_barrier
	v_mov_b32_e32 v71, v100
	ds_read2_b32 v[100:101], v92 offset1:1
	ds_read2_b32 v[102:103], v92 offset0:2 offset1:3
	v_lshl_add_u64 v[70:71], v[70:71], 1, s[8:9]
	s_ashr_i32 s11, s10, 31
	v_lshl_add_u64 v[70:71], s[10:11], 1, v[70:71]
	v_mov_b32_e32 v69, v1
	v_lshl_add_u64 v[70:71], v[70:71], 0, v[68:69]
	s_waitcnt lgkmcnt(0)
	global_store_dwordx4 v[70:71], v[100:103], off
	ds_read2_b32 v[100:101], v92 offset0:4 offset1:5
	ds_read2_b32 v[102:103], v92 offset0:6 offset1:7
	s_andn2_b64 vcc, exec, s[18:19]
	s_waitcnt lgkmcnt(0)
	global_store_dwordx4 v[70:71], v[100:103], off offset:16
	ds_read2_b32 v[100:101], v92 offset0:8 offset1:9
	ds_read2_b32 v[102:103], v92 offset0:10 offset1:11
	s_waitcnt lgkmcnt(0)
	global_store_dwordx4 v[70:71], v[100:103], off offset:32
	ds_read2_b32 v[100:101], v92 offset0:12 offset1:13
	ds_read2_b32 v[102:103], v92 offset0:14 offset1:15
	s_waitcnt lgkmcnt(0)
	global_store_dwordx4 v[70:71], v[100:103], off offset:48
	s_barrier
	s_cbranch_vccnz .LBB0_1145
	s_waitcnt vmcnt(0)
	v_mov_b32_e32 v87, v0
	v_mov_b32_e32 v85, v99
	v_mov_b32_e32 v83, v98
	v_mov_b32_e32 v81, v97
	v_mov_b32_e32 v79, v96
	v_mov_b32_e32 v77, v95
	v_mov_b32_e32 v76, v94
	v_mov_b32_e32 v74, v93
	s_mov_b32 s14, s7
	s_mov_b32 s10, s40
	s_mov_b32 s13, s6
	s_mov_b64 s[8:9], s[20:21]
	s_mov_b32 s12, s3
	v_mov_b32_e32 v2, v34
	v_mov_b32_e32 v3, v35
	v_mov_b32_e32 v4, v36
	v_mov_b32_e32 v5, v37
	v_mov_b32_e32 v6, v38
	v_mov_b32_e32 v7, v39
	v_mov_b32_e32 v8, v40
	v_mov_b32_e32 v9, v41
	v_mov_b32_e32 v10, v42
	v_mov_b32_e32 v11, v43
	v_mov_b32_e32 v12, v44
	v_mov_b32_e32 v13, v45
	v_mov_b32_e32 v14, v46
	v_mov_b32_e32 v15, v47
	v_mov_b32_e32 v16, v48
	v_mov_b32_e32 v17, v49
	v_mov_b32_e32 v18, v50
	v_mov_b32_e32 v19, v51
	v_mov_b32_e32 v20, v52
	v_mov_b32_e32 v21, v53
	v_mov_b32_e32 v22, v54
	v_mov_b32_e32 v23, v55
	v_mov_b32_e32 v24, v56
	v_mov_b32_e32 v25, v57
	v_mov_b32_e32 v26, v58
	v_mov_b32_e32 v27, v59
	v_mov_b32_e32 v28, v60
	v_mov_b32_e32 v29, v61
	v_mov_b32_e32 v30, v62
	v_mov_b32_e32 v31, v63
	v_mov_b32_e32 v32, v64
	v_mov_b32_e32 v33, v65
	s_branch .LBB0_1145
